# v62 + 64-byte alignment of the hot non-GEMM loop heads (P2 sample/hgA/S5 loops, P3 scan, P4 unit loop and hgC)
# speedup vs baseline: 1.0032x; 1.0032x over previous
; #define GAS __attribute__((address_space(1)))
; #define LAS __attribute__((address_space(3)))
; __device__ __forceinline__ void hgrn_sample_loop(Frame& F) {
;     ...
;         f32x4 vr[8], o[8];
; #pragma unroll
;         for (int t = 0; t < 8; ++t) { vr[t] = *(const LAS f32x4*)(Vs + t * 128 + v4); o[t] = (f32x4){0.f, 0.f, 0.f, 0.f}; }
; #pragma unroll
;         for (int j = 0; j < 8; ++j) { const int k = 8 * kg + j; const f32x4 sv = s0[j]; const f32x4 qa = *(const LAS f32x4*)(QT + k * 8), qb = *(const LAS f32x4*)(QT + k * 8 + 4), ka = *(const LAS f32x4*)(K3T + k * 8), kb = *(const LAS f32x4*)(K3T + k * 8 + 4);
;             f32x4 sn = sv * DEC[k];
;             o[0] += sv * qa.x; o[1] += sv * qa.y; o[2] += sv * qa.z; o[3] += sv * qa.w; o[4] += sv * qb.x; o[5] += sv * qb.y; o[6] += sv * qb.z; o[7] += sv * qb.w;
;             sn += vr[0] * ka.x; sn += vr[1] * ka.y; sn += vr[2] * ka.z; sn += vr[3] * ka.w; sn += vr[4] * kb.x; sn += vr[5] * kb.y; sn += vr[6] * kb.z; sn += vr[7] * kb.w;
;             *(GAS f32x4*)(Sout + (size_t)k * HD + v4) = sn; }
.LBB0_279:
	v_pk_fma_f32 v[176:177], v[30:31], v[70:71], 0 op_sel_hi:[1,0,0]
	v_pk_fma_f32 v[178:179], v[32:33], v[70:71], 0 op_sel_hi:[1,0,0]
	v_pk_fma_f32 v[180:181], v[30:31], v[70:71], 0 op_sel:[0,1,0] op_sel_hi:[1,1,0]
	v_pk_fma_f32 v[70:71], v[32:33], v[70:71], 0 op_sel:[0,1,0] op_sel_hi:[1,1,0]
	v_pk_fma_f32 v[182:183], v[32:33], v[72:73], 0 op_sel_hi:[1,0,0]
	v_pk_fma_f32 v[184:185], v[30:31], v[72:73], 0 op_sel_hi:[1,0,0]
	v_mov_b32_e32 v72, v73
	v_pk_fma_f32 v[194:195], v[32:33], v[68:69], 0 op_sel_hi:[1,0,0]
	v_pk_fma_f32 v[196:197], v[30:31], v[68:69], 0 op_sel_hi:[1,0,0]
	v_mov_b32_e32 v68, v69
	v_pk_fma_f32 v[186:187], v[32:33], v[72:73], 0 op_sel_hi:[1,0,0]
	v_pk_fma_f32 v[72:73], v[30:31], v[72:73], 0 op_sel_hi:[1,0,0]
	v_pk_fma_f32 v[188:189], v[30:31], v[66:67], 0 op_sel_hi:[1,0,0]
	v_pk_fma_f32 v[190:191], v[32:33], v[66:67], 0 op_sel_hi:[1,0,0]
	v_pk_fma_f32 v[192:193], v[30:31], v[66:67], 0 op_sel:[0,1,0] op_sel_hi:[1,1,0]
	v_pk_fma_f32 v[66:67], v[32:33], v[66:67], 0 op_sel:[0,1,0] op_sel_hi:[1,1,0]
	v_pk_fma_f32 v[32:33], v[32:33], v[68:69], 0 op_sel_hi:[1,0,0]
	v_pk_fma_f32 v[30:31], v[30:31], v[68:69], 0 op_sel_hi:[1,0,0]
	v_pk_fma_f32 v[68:69], v[28:29], v[86:87], v[178:179] op_sel_hi:[1,0,1]
	v_pk_fma_f32 v[176:177], v[26:27], v[86:87], v[176:177] op_sel_hi:[1,0,1]
	v_pk_fma_f32 v[70:71], v[28:29], v[86:87], v[70:71] op_sel:[0,1,0]
	v_pk_fma_f32 v[86:87], v[26:27], v[86:87], v[180:181] op_sel:[0,1,0]
	v_pk_fma_f32 v[178:179], v[28:29], v[88:89], v[182:183] op_sel_hi:[1,0,1]
	v_pk_fma_f32 v[180:181], v[26:27], v[88:89], v[184:185] op_sel_hi:[1,0,1]
	v_mov_b32_e32 v88, v89
	v_pk_fma_f32 v[182:183], v[28:29], v[88:89], v[186:187] op_sel_hi:[1,0,1]
	v_pk_fma_f32 v[72:73], v[26:27], v[88:89], v[72:73] op_sel_hi:[1,0,1]
	v_pk_fma_f32 v[88:89], v[28:29], v[74:75], v[190:191] op_sel_hi:[1,0,1]
	v_pk_fma_f32 v[184:185], v[26:27], v[74:75], v[188:189] op_sel_hi:[1,0,1]
	v_pk_fma_f32 v[66:67], v[28:29], v[74:75], v[66:67] op_sel:[0,1,0]
	v_pk_fma_f32 v[74:75], v[26:27], v[74:75], v[192:193] op_sel:[0,1,0]
	v_pk_fma_f32 v[186:187], v[28:29], v[76:77], v[194:195] op_sel_hi:[1,0,1]
	v_pk_fma_f32 v[188:189], v[26:27], v[76:77], v[196:197] op_sel_hi:[1,0,1]
	v_mov_b32_e32 v76, v77
	v_pk_fma_f32 v[28:29], v[28:29], v[76:77], v[32:33] op_sel_hi:[1,0,1]
	v_pk_fma_f32 v[26:27], v[26:27], v[76:77], v[30:31] op_sel_hi:[1,0,1]
	v_pk_fma_f32 v[30:31], v[24:25], v[94:95], v[68:69] op_sel_hi:[1,0,1]
	v_pk_fma_f32 v[32:33], v[22:23], v[94:95], v[176:177] op_sel_hi:[1,0,1]
	v_pk_fma_f32 v[68:69], v[24:25], v[94:95], v[70:71] op_sel:[0,1,0]
	v_pk_fma_f32 v[70:71], v[22:23], v[94:95], v[86:87] op_sel:[0,1,0]
	v_pk_fma_f32 v[76:77], v[22:23], v[96:97], v[180:181] op_sel_hi:[1,0,1]
	v_pk_fma_f32 v[86:87], v[24:25], v[96:97], v[178:179] op_sel_hi:[1,0,1]
	v_mov_b32_e32 v94, v97
	v_pk_fma_f32 v[88:89], v[24:25], v[78:79], v[88:89] op_sel_hi:[1,0,1]
	v_pk_fma_f32 v[96:97], v[22:23], v[78:79], v[184:185] op_sel_hi:[1,0,1]
	v_pk_fma_f32 v[66:67], v[24:25], v[78:79], v[66:67] op_sel:[0,1,0]
	v_pk_fma_f32 v[74:75], v[22:23], v[78:79], v[74:75] op_sel:[0,1,0]
	v_pk_fma_f32 v[78:79], v[22:23], v[80:81], v[188:189] op_sel_hi:[1,0,1]
	v_pk_fma_f32 v[176:177], v[24:25], v[80:81], v[186:187] op_sel_hi:[1,0,1]
	v_mov_b32_e32 v80, v81
	v_pk_fma_f32 v[72:73], v[22:23], v[94:95], v[72:73] op_sel_hi:[1,0,1]
	v_pk_fma_f32 v[94:95], v[24:25], v[94:95], v[182:183] op_sel_hi:[1,0,1]
	v_pk_fma_f32 v[24:25], v[24:25], v[80:81], v[28:29] op_sel_hi:[1,0,1]
	v_pk_fma_f32 v[28:29], v[18:19], v[98:99], v[32:33] op_sel_hi:[1,0,1]
	v_pk_fma_f32 v[32:33], v[18:19], v[98:99], v[70:71] op_sel:[0,1,0]
	v_pk_fma_f32 v[70:71], v[18:19], v[100:101], v[76:77] op_sel_hi:[1,0,1]
	v_mov_b32_e32 v76, v101
	v_pk_fma_f32 v[22:23], v[22:23], v[80:81], v[26:27] op_sel_hi:[1,0,1]
	v_pk_fma_f32 v[26:27], v[20:21], v[98:99], v[30:31] op_sel_hi:[1,0,1]
	v_pk_fma_f32 v[30:31], v[20:21], v[98:99], v[68:69] op_sel:[0,1,0]
	v_pk_fma_f32 v[68:69], v[20:21], v[100:101], v[86:87] op_sel_hi:[1,0,1]
	v_pk_fma_f32 v[80:81], v[20:21], v[76:77], v[94:95] op_sel_hi:[1,0,1]
	v_pk_fma_f32 v[72:73], v[18:19], v[76:77], v[72:73] op_sel_hi:[1,0,1]
	v_pk_fma_f32 v[76:77], v[20:21], v[82:83], v[88:89] op_sel_hi:[1,0,1]
	v_pk_fma_f32 v[86:87], v[18:19], v[82:83], v[96:97] op_sel_hi:[1,0,1]
	v_pk_fma_f32 v[66:67], v[20:21], v[82:83], v[66:67] op_sel:[0,1,0]
	v_pk_fma_f32 v[74:75], v[18:19], v[82:83], v[74:75] op_sel:[0,1,0]
	v_pk_fma_f32 v[82:83], v[20:21], v[84:85], v[176:177] op_sel_hi:[1,0,1]
	v_pk_fma_f32 v[78:79], v[18:19], v[84:85], v[78:79] op_sel_hi:[1,0,1]
	v_mov_b32_e32 v84, v85
	v_pk_fma_f32 v[20:21], v[20:21], v[84:85], v[24:25] op_sel_hi:[1,0,1]
	v_pk_fma_f32 v[24:25], v[14:15], v[102:103], v[28:29] op_sel_hi:[1,0,1]
	v_pk_fma_f32 v[28:29], v[14:15], v[102:103], v[32:33] op_sel:[0,1,0]
	v_pk_fma_f32 v[32:33], v[16:17], v[104:105], v[68:69] op_sel_hi:[1,0,1]
	v_mov_b32_e32 v68, v105
	v_pk_fma_f32 v[18:19], v[18:19], v[84:85], v[22:23] op_sel_hi:[1,0,1]
	v_pk_fma_f32 v[22:23], v[16:17], v[102:103], v[26:27] op_sel_hi:[1,0,1]
	v_pk_fma_f32 v[26:27], v[16:17], v[102:103], v[30:31] op_sel:[0,1,0]
	v_pk_fma_f32 v[30:31], v[14:15], v[104:105], v[70:71] op_sel_hi:[1,0,1]
	v_pk_fma_f32 v[70:71], v[14:15], v[68:69], v[72:73] op_sel_hi:[1,0,1]
	v_pk_fma_f32 v[68:69], v[16:17], v[68:69], v[80:81] op_sel_hi:[1,0,1]
	v_pk_fma_f32 v[80:81], v[16:17], v[92:93], v[82:83] op_sel_hi:[1,0,1]
	v_mov_b32_e32 v82, v93
	v_pk_fma_f32 v[72:73], v[16:17], v[90:91], v[76:77] op_sel_hi:[1,0,1]
	v_pk_fma_f32 v[76:77], v[14:15], v[90:91], v[86:87] op_sel_hi:[1,0,1]
	v_pk_fma_f32 v[66:67], v[16:17], v[90:91], v[66:67] op_sel:[0,1,0]
; #define GAS __attribute__((address_space(1)))
; #define LAS __attribute__((address_space(3)))
; __device__ __forceinline__ void hgrn_sample_loop(Frame& F) {
;     ...
;         for (int j = 0; j < 8; ++j) { const int k = 8 * kg + j; const f32x4 sv = s0[j]; const f32x4 qa = *(const LAS f32x4*)(QT + k * 8), qb = *(const LAS f32x4*)(QT + k * 8 + 4), ka = *(const LAS f32x4*)(K3T + k * 8), kb = *(const LAS f32x4*)(K3T + k * 8 + 4);
;             f32x4 sn = sv * DEC[k];
;             o[0] += sv * qa.x; o[1] += sv * qa.y; o[2] += sv * qa.z; o[3] += sv * qa.w; o[4] += sv * qb.x; o[5] += sv * qb.y; o[6] += sv * qb.z; o[7] += sv * qb.w;
;             sn += vr[0] * ka.x; sn += vr[1] * ka.y; sn += vr[2] * ka.z; sn += vr[3] * ka.w; sn += vr[4] * kb.x; sn += vr[5] * kb.y; sn += vr[6] * kb.z; sn += vr[7] * kb.w;
;             *(GAS f32x4*)(Sout + (size_t)k * HD + v4) = sn; }
;         if (idx + F.G < SB_B * HH) {
; #pragma unroll
;             for (int j = 0; j < 8; ++j) s0[j] = *(const GAS f32x4*)(F.in[4] + (size_t)(idx + F.G) * HD * HD + (size_t)(8 * kg + j) * HD + v4); }
; #pragma unroll
;         for (int t = 0; t < 8; ++t) *(LAS f32x4*)(OP + (kg * 8 + t) * 128 + v4) = o[t];
;         __syncthreads();
	v_pk_fma_f32 v[78:79], v[14:15], v[92:93], v[78:79] op_sel_hi:[1,0,1]
	v_pk_fma_f32 v[16:17], v[16:17], v[82:83], v[20:21] op_sel_hi:[1,0,1]
	v_pk_fma_f32 v[20:21], v[10:11], v[110:111], v[24:25] op_sel_hi:[1,0,1]
	v_pk_fma_f32 v[24:25], v[10:11], v[110:111], v[28:29] op_sel:[0,1,0]
	v_pk_fma_f32 v[28:29], v[10:11], v[112:113], v[30:31] op_sel_hi:[1,0,1]
	v_mov_b32_e32 v30, v113
	v_pk_fma_f32 v[74:75], v[14:15], v[90:91], v[74:75] op_sel:[0,1,0]
	v_pk_fma_f32 v[14:15], v[14:15], v[82:83], v[18:19] op_sel_hi:[1,0,1]
	v_pk_fma_f32 v[18:19], v[12:13], v[110:111], v[22:23] op_sel_hi:[1,0,1]
	v_pk_fma_f32 v[22:23], v[12:13], v[110:111], v[26:27] op_sel:[0,1,0]
	v_pk_fma_f32 v[26:27], v[12:13], v[112:113], v[32:33] op_sel_hi:[1,0,1]
	v_pk_fma_f32 v[32:33], v[12:13], v[30:31], v[68:69] op_sel_hi:[1,0,1]
	v_pk_fma_f32 v[30:31], v[10:11], v[30:31], v[70:71] op_sel_hi:[1,0,1]
	v_pk_fma_f32 v[70:71], v[10:11], v[106:107], v[76:77] op_sel_hi:[1,0,1]
	v_pk_fma_f32 v[76:77], v[10:11], v[108:109], v[78:79] op_sel_hi:[1,0,1]
	v_mov_b32_e32 v78, v109
	v_pk_fma_f32 v[68:69], v[12:13], v[106:107], v[72:73] op_sel_hi:[1,0,1]
	v_pk_fma_f32 v[66:67], v[12:13], v[106:107], v[66:67] op_sel:[0,1,0]
	v_pk_fma_f32 v[72:73], v[10:11], v[106:107], v[74:75] op_sel:[0,1,0]
	v_pk_fma_f32 v[74:75], v[12:13], v[108:109], v[80:81] op_sel_hi:[1,0,1]
	v_pk_fma_f32 v[12:13], v[12:13], v[78:79], v[16:17] op_sel_hi:[1,0,1]
	v_pk_fma_f32 v[16:17], v[6:7], v[118:119], v[20:21] op_sel_hi:[1,0,1]
	v_pk_fma_f32 v[20:21], v[6:7], v[118:119], v[24:25] op_sel:[0,1,0]
	v_pk_fma_f32 v[24:25], v[8:9], v[120:121], v[26:27] op_sel_hi:[1,0,1]
	v_mov_b32_e32 v26, v121
	v_pk_fma_f32 v[10:11], v[10:11], v[78:79], v[14:15] op_sel_hi:[1,0,1]
	v_pk_fma_f32 v[14:15], v[8:9], v[118:119], v[18:19] op_sel_hi:[1,0,1]
	v_pk_fma_f32 v[18:19], v[8:9], v[118:119], v[22:23] op_sel:[0,1,0]
	v_pk_fma_f32 v[22:23], v[6:7], v[120:121], v[28:29] op_sel_hi:[1,0,1]
	v_pk_fma_f32 v[28:29], v[6:7], v[26:27], v[30:31] op_sel_hi:[1,0,1]
	v_pk_fma_f32 v[30:31], v[8:9], v[114:115], v[68:69] op_sel_hi:[1,0,1]
	v_pk_fma_f32 v[68:69], v[6:7], v[114:115], v[72:73] op_sel:[0,1,0]
	v_pk_fma_f32 v[72:73], v[8:9], v[116:117], v[74:75] op_sel_hi:[1,0,1]
	v_mov_b32_e32 v74, v117
	v_pk_fma_f32 v[26:27], v[8:9], v[26:27], v[32:33] op_sel_hi:[1,0,1]
	v_pk_fma_f32 v[32:33], v[6:7], v[114:115], v[70:71] op_sel_hi:[1,0,1]
	v_pk_fma_f32 v[66:67], v[8:9], v[114:115], v[66:67] op_sel:[0,1,0]
	v_pk_fma_f32 v[70:71], v[6:7], v[116:117], v[76:77] op_sel_hi:[1,0,1]
	v_pk_fma_f32 v[76:77], v[6:7], v[74:75], v[10:11] op_sel_hi:[1,0,1]
	v_pk_fma_f32 v[74:75], v[8:9], v[74:75], v[12:13] op_sel_hi:[1,0,1]
	v_pk_fma_f32 v[12:13], v[4:5], v[126:127], v[18:19] op_sel:[0,1,0]
	v_mov_b32_e32 v18, v129
	v_pk_fma_f32 v[10:11], v[2:3], v[126:127], v[20:21] op_sel:[0,1,0]
	v_pk_fma_f32 v[20:21], v[4:5], v[18:19], v[26:27] op_sel_hi:[1,0,1]
	v_pk_fma_f32 v[18:19], v[2:3], v[18:19], v[28:29] op_sel_hi:[1,0,1]
	v_pk_fma_f32 v[28:29], v[4:5], v[122:123], v[66:67] op_sel:[0,1,0]
	v_mov_b32_e32 v66, v125
	v_pk_fma_f32 v[8:9], v[4:5], v[126:127], v[14:15] op_sel_hi:[1,0,1]
	v_pk_fma_f32 v[6:7], v[2:3], v[126:127], v[16:17] op_sel_hi:[1,0,1]
	v_pk_fma_f32 v[16:17], v[4:5], v[128:129], v[24:25] op_sel_hi:[1,0,1]
	v_pk_fma_f32 v[14:15], v[2:3], v[128:129], v[22:23] op_sel_hi:[1,0,1]
	v_pk_fma_f32 v[24:25], v[4:5], v[122:123], v[30:31] op_sel_hi:[1,0,1]
	v_pk_fma_f32 v[22:23], v[2:3], v[122:123], v[32:33] op_sel_hi:[1,0,1]
	v_pk_fma_f32 v[26:27], v[2:3], v[122:123], v[68:69] op_sel:[0,1,0]
	v_pk_fma_f32 v[32:33], v[4:5], v[124:125], v[72:73] op_sel_hi:[1,0,1]
	v_pk_fma_f32 v[30:31], v[2:3], v[124:125], v[70:71] op_sel_hi:[1,0,1]
	v_pk_fma_f32 v[4:5], v[4:5], v[66:67], v[74:75] op_sel_hi:[1,0,1]
	v_pk_fma_f32 v[2:3], v[2:3], v[66:67], v[76:77] op_sel_hi:[1,0,1]
	v_add_u32_e32 v66, v131, v132
	ds_write_b128 v66, v[6:9] offset:25344
	ds_write_b128 v66, v[10:13] offset:25856
	ds_write_b128 v66, v[14:17] offset:26368
	ds_write_b128 v66, v[18:21] offset:26880
	ds_write_b128 v66, v[22:25] offset:27392
	ds_write_b128 v66, v[26:29] offset:27904
	ds_write_b128 v66, v[30:33] offset:28416
	ds_write_b128 v66, v[2:5] offset:28928
	s_waitcnt lgkmcnt(0)
	s_barrier
; __device__ __forceinline__ unsigned pk2(float lo, float hi) { f32x2_t v = {lo, hi}; bf16x2_t h = __builtin_convertvector(v, bf16x2_t); return __builtin_bit_cast(unsigned, h); }
; __device__ __forceinline__ float siluf_(float x) { return x * __builtin_amdgcn_rcpf(1.0f + __builtin_amdgcn_exp2f(-1.4426950408889634f * x)); }
; __device__ __forceinline__ void hgrn_sample_loop(Frame& F) {
;     ...
;         __syncthreads();
; #pragma unroll
;         for (int r = 0; r < 2; ++r) { const int e = tid + 512 * r, t = e >> 7, vv = e & 127; float acc = 0.f;
; #pragma unroll
;             for (int g2 = 0; g2 < 16; ++g2) acc += OP[(g2 * 8 + t) * 128 + vv];
; #pragma unroll
;             for (int s = 0; s < 8; ++s) acc += ATT[t * 8 + s] * Vs[s * 128 + vv];
;             OT[t * 128 + vv] = acc; }
;         __syncthreads();
;         { const int t = F.wave, lane = F.lane; const float o0 = OT[t * 128 + 2 * lane], o1 = OT[t * 128 + 2 * lane + 1];
;           const float rstd = __builtin_amdgcn_rsqf(wave_sum(o0 * o0 + o1 * o1) * (1.0f / HD) + EPS);
;           const unsigned gw2 = *(const unsigned*)(PB + (size_t)(tok0 + t) * PBW + 1536 + h * HD + 2 * lane);
;           const float g0 = F.in[17][2 * lane], g1 = F.in[17][2 * lane + 1];
;           *(unsigned*)(MIX + (size_t)(tok0 + t) * DM + 512 + h * HD + 2 * lane) = pk2(o0 * rstd * g0 * siluf_(bflo(gw2)), o1 * rstd * g1 * siluf_(bfhi(gw2))); }
;         __syncthreads();
	ds_read2st64_b32 v[2:3], v167 offset0:99 offset1:115
	ds_read2st64_b32 v[4:5], v167 offset0:131 offset1:147
	ds_read2st64_b32 v[6:7], v167 offset0:163 offset1:179
	s_add_i32 s4, s96, s4
	s_ashr_i32 s5, s4, 31
	s_waitcnt lgkmcnt(2)
	v_add_f32_e32 v2, 0, v2
	v_add_f32_e32 v2, v2, v3
	s_waitcnt lgkmcnt(1)
	v_add_f32_e32 v4, v2, v4
	ds_read2st64_b32 v[2:3], v167 offset0:195 offset1:211
	v_add_f32_e32 v4, v4, v5
	s_waitcnt lgkmcnt(1)
	v_add_f32_e32 v6, v4, v6
	ds_read2st64_b32 v[4:5], v167 offset0:227 offset1:243
	v_add_f32_e32 v6, v6, v7
	s_waitcnt lgkmcnt(1)
	v_add_f32_e32 v2, v6, v2
	ds_read2st64_b32 v[6:7], v168 offset0:160 offset1:176
	v_add_f32_e32 v2, v2, v3
	s_waitcnt lgkmcnt(1)
	v_add_f32_e32 v4, v2, v4
	ds_read2st64_b32 v[2:3], v168 offset0:192 offset1:208
	v_add_f32_e32 v4, v4, v5
	s_waitcnt lgkmcnt(1)
	v_add_f32_e32 v4, v4, v6
	v_add_f32_e32 v4, v4, v7
	ds_read2st64_b32 v[6:7], v168 offset0:224 offset1:240
	s_waitcnt lgkmcnt(1)
	v_add_f32_e32 v2, v4, v2
	v_add_f32_e32 v8, v2, v3
	ds_read_b128 v[2:5], v173 offset:20992
	ds_read2st64_b32 v[10:11], v155 offset0:64 offset1:66
	s_lshl_b64 s[16:17], s[4:5], 12
	s_waitcnt lgkmcnt(2)
	v_add_f32_e32 v6, v8, v6
	v_add_f32_e32 v18, v6, v7
	ds_read2st64_b32 v[12:13], v155 offset0:68 offset1:70
	ds_read_b128 v[6:9], v173 offset:21008
	s_waitcnt lgkmcnt(2)
	v_fmac_f32_e32 v18, v2, v10
	ds_read2st64_b32 v[14:15], v155 offset0:72 offset1:74
	v_fmac_f32_e32 v18, v3, v11
	ds_read2st64_b32 v[2:3], v169 offset0:99 offset1:115
	s_waitcnt lgkmcnt(3)
	v_fmac_f32_e32 v18, v4, v12
	v_fmac_f32_e32 v18, v5, v13
	ds_read2st64_b32 v[4:5], v169 offset0:131 offset1:147
	s_waitcnt lgkmcnt(2)
	v_fmac_f32_e32 v18, v6, v14
	v_fmac_f32_e32 v18, v7, v15
	s_waitcnt lgkmcnt(1)
	v_add_f32_e32 v2, 0, v2
	ds_read2st64_b32 v[6:7], v169 offset0:163 offset1:179
	v_add_f32_e32 v2, v2, v3
	s_waitcnt lgkmcnt(1)
	v_add_f32_e32 v4, v2, v4
	ds_read2st64_b32 v[2:3], v169 offset0:195 offset1:211
	ds_read2st64_b32 v[16:17], v155 offset0:76 offset1:78
	v_add_f32_e32 v4, v4, v5
	s_waitcnt lgkmcnt(2)
	v_add_f32_e32 v6, v4, v6
	ds_read2st64_b32 v[4:5], v169 offset0:227 offset1:243
	v_add_f32_e32 v6, v6, v7
	s_waitcnt lgkmcnt(2)
	v_add_f32_e32 v2, v6, v2
	ds_read2st64_b32 v[6:7], v170 offset0:160 offset1:176
	s_waitcnt lgkmcnt(2)
	v_fmac_f32_e32 v18, v8, v16
	v_fmac_f32_e32 v18, v9, v17
	v_add_f32_e32 v2, v2, v3
	ds_read2st64_b32 v[8:9], v170 offset0:192 offset1:208
	s_waitcnt lgkmcnt(2)
	v_add_f32_e32 v2, v2, v4
	v_add_f32_e32 v2, v2, v5
	ds_write_b32 v146, v18 offset:21248
	s_waitcnt lgkmcnt(2)
	v_add_f32_e32 v2, v2, v6
	ds_read2st64_b32 v[18:19], v170 offset0:224 offset1:240
	v_add_f32_e32 v2, v2, v7
	s_waitcnt lgkmcnt(2)
	v_add_f32_e32 v6, v2, v8
	ds_read_b128 v[2:5], v174 offset:20992
	v_add_f32_e32 v6, v6, v9
	s_waitcnt lgkmcnt(1)
	v_add_f32_e32 v6, v6, v18
	v_add_f32_e32 v18, v6, v19
	ds_read_b128 v[6:9], v174 offset:21008
	s_waitcnt lgkmcnt(1)
	v_fmac_f32_e32 v18, v2, v10
	v_fmac_f32_e32 v18, v3, v11
	v_fmac_f32_e32 v18, v4, v12
	v_fmac_f32_e32 v18, v5, v13
	s_waitcnt lgkmcnt(0)
	v_fmac_f32_e32 v18, v6, v14
	s_add_u32 s16, s56, s16
	v_fmac_f32_e32 v18, v7, v15
	s_addc_u32 s17, s57, s17
	s_lshl_b32 s18, s35, 8
	v_fmac_f32_e32 v18, v8, v16
	s_add_u32 s16, s16, s18
	v_fmac_f32_e32 v18, v9, v17
	s_addc_u32 s17, s17, 0
	ds_write_b32 v146, v18 offset:23296
	s_waitcnt lgkmcnt(0)
	s_barrier
	global_load_dword v8, v134, s[16:17] offset:3072
	global_load_dwordx2 v[2:3], v[136:137], off
	ds_read_b64 v[4:5], v171 offset:21248
	s_lshl_b64 s[4:5], s[4:5], 11
	s_add_u32 s4, s50, s4
	s_addc_u32 s5, s51, s5
	s_add_u32 s4, s4, s18
	s_waitcnt lgkmcnt(0)
	v_pk_mul_f32 v[6:7], v[4:5], v[4:5]
	s_addc_u32 s5, s5, 0
	v_add_f32_e32 v6, v6, v7
	ds_bpermute_b32 v7, v150, v6
	s_waitcnt vmcnt(9)
	v_mov_b64_e32 v[30:31], v[34:35]
	s_waitcnt vmcnt(8)
	v_mov_b64_e32 v[26:27], v[38:39]
	s_waitcnt vmcnt(7)
	v_mov_b64_e32 v[22:23], v[42:43]
	s_waitcnt vmcnt(6)
	v_mov_b64_e32 v[18:19], v[46:47]
	s_waitcnt lgkmcnt(0)
	v_add_f32_e32 v6, v6, v7
	ds_bpermute_b32 v7, v151, v6
	s_waitcnt vmcnt(5)
	v_mov_b64_e32 v[14:15], v[50:51]
	v_lshl_add_u64 v[140:141], v[140:141], 0, s[12:13]
	s_add_i32 s3, s3, s33
	v_lshl_add_u64 v[142:143], v[142:143], 0, s[12:13]
	s_waitcnt lgkmcnt(0)
	v_add_f32_e32 v6, v6, v7
	ds_bpermute_b32 v7, v152, v6
	v_mov_b64_e32 v[32:33], v[36:37]
	v_mov_b64_e32 v[28:29], v[40:41]
	v_mov_b64_e32 v[24:25], v[44:45]
	v_mov_b64_e32 v[20:21], v[48:49]
	s_waitcnt lgkmcnt(0)
	v_add_f32_e32 v6, v6, v7
	ds_bpermute_b32 v7, v156, v6
	v_mov_b64_e32 v[16:17], v[52:53]
	s_waitcnt lgkmcnt(0)
	v_add_f32_e32 v6, v6, v7
	ds_bpermute_b32 v7, v157, v6
	s_waitcnt lgkmcnt(0)
	v_add_f32_e32 v9, v6, v7
	ds_bpermute_b32 v10, v158, v9
	s_waitcnt vmcnt(1)
	v_lshlrev_b32_e32 v6, 16, v8
	v_and_b32_e32 v7, 0xffff0000, v8
	s_waitcnt lgkmcnt(0)
	v_add_f32_e32 v8, v9, v10
	v_mul_f32_e32 v9, 0xbfb8aa3b, v6
	v_exp_f32_e32 v9, v9
	v_mul_f32_e32 v10, 0xbfb8aa3b, v7
	v_exp_f32_e32 v11, v10
	v_fmamk_f32 v8, v8, 0x3c000000, v175
	v_add_f32_e32 v9, 1.0, v9
	v_rsq_f32_e32 v8, v8
	v_rcp_f32_e32 v10, v9
	v_add_f32_e32 v9, 1.0, v11
	v_rcp_f32_e32 v11, v9
	v_pk_mul_f32 v[4:5], v[4:5], v[8:9] op_sel_hi:[1,0]
	s_waitcnt vmcnt(0)
	v_pk_mul_f32 v[2:3], v[2:3], v[4:5]
	v_pk_mul_f32 v[4:5], v[10:11], v[6:7]
	v_mov_b64_e32 v[10:11], v[54:55]
	v_pk_mul_f32 v[2:3], v[2:3], v[4:5]
	v_mov_b64_e32 v[6:7], v[58:59]
	v_cvt_pk_bf16_f32 v4, v2, v3
	v_lshl_add_u64 v[2:3], s[4:5], 0, v[134:135]
	v_add_co_u32_e32 v2, vcc, 0xc500000, v2
	v_mov_b64_e32 v[12:13], v[56:57]
	s_nop 0
	v_addc_co_u32_e32 v3, vcc, 0, v3, vcc
	global_store_dword v[2:3], v4, off offset:1024
	v_mov_b64_e32 v[2:3], v[62:63]
	s_andn2_b64 vcc, exec, s[14:15]
	v_mov_b64_e32 v[8:9], v[60:61]
	v_mov_b64_e32 v[4:5], v[64:65]
	s_barrier
	s_cbranch_vccz .LBB0_294
	.p2align	6

; __device__ __forceinline__ unsigned pk2(float lo, float hi) { f32x2_t v = {lo, hi}; bf16x2_t h = __builtin_convertvector(v, bf16x2_t); return __builtin_bit_cast(unsigned, h); }
; __device__ __forceinline__ void hgA_loop(Frame& F, int j0, int j1) {
;     ...
;           v4u w0, w1; w0.x = pk2(acc[0], acc[1]); w0.y = pk2(acc[2], acc[3]); w0.z = pk2(acc[4], acc[5]); w0.w = pk2(acc[6], acc[7]); w1.x = pk2(acc[8], acc[9]); w1.y = pk2(acc[10], acc[11]); w1.z = pk2(acc[12], acc[13]); w1.w = pk2(acc[14], acc[15]);
;           v4u* d = (v4u*)(OI + (size_t)(wave * 64 + lane) * 16); d[0] = w0; d[1] = w1; }
;         __syncthreads();
.LBB0_298:
	s_nop 10
	v_cvt_pk_bf16_f32 v2, v2, v3
	v_cvt_pk_bf16_f32 v3, v4, v5
	v_cvt_pk_bf16_f32 v4, v6, v7
	v_cvt_pk_bf16_f32 v6, v10, v11
	v_lshl_add_u64 v[10:11], s[58:59], 0, v[32:33]
	s_mov_b32 s44, 0x1000000
	v_add_co_u32_e32 v10, vcc, s44, v10
	s_add_i32 s63, s63, s76
	s_add_i32 s77, s77, s78
	s_add_i32 s62, s62, s79
	v_cvt_pk_bf16_f32 v5, v8, v9
	v_cvt_pk_bf16_f32 v8, v14, v15
	v_cvt_pk_bf16_f32 v9, v16, v17
	v_addc_co_u32_e32 v11, vcc, 0, v11, vcc
	s_add_u32 s58, s58, s86
	v_cvt_pk_bf16_f32 v7, v12, v13
	global_store_dwordx4 v[10:11], v[2:5], off
	global_store_dwordx4 v[10:11], v[6:9], off offset:16
	s_addc_u32 s59, s59, s87
	v_lshl_add_u64 v[34:35], v[34:35], 0, s[88:89]
	v_lshl_add_u64 v[36:37], v[36:37], 0, s[4:5]
	s_andn2_b64 vcc, exec, s[54:55]
	s_waitcnt vmcnt(54)
	v_mov_b32_e32 v8, v86
	s_waitcnt vmcnt(52)
	v_mov_b32_e32 v9, v87
	s_waitcnt vmcnt(50)
	v_mov_b32_e32 v10, v89
	s_waitcnt vmcnt(48)
	v_mov_b32_e32 v11, v92
	s_waitcnt vmcnt(46)
	v_mov_b32_e32 v12, v94
	s_waitcnt vmcnt(44)
	v_mov_b32_e32 v13, v95
	s_waitcnt vmcnt(42)
	v_mov_b32_e32 v14, v96
	s_waitcnt vmcnt(40)
	v_mov_b32_e32 v15, v97
	s_waitcnt vmcnt(38)
	v_mov_b32_e32 v16, v98
	s_waitcnt vmcnt(36)
	v_mov_b32_e32 v17, v99
	s_waitcnt vmcnt(34)
	v_mov_b32_e32 v106, v100
	s_waitcnt vmcnt(32)
	v_mov_b32_e32 v107, v101
	s_waitcnt vmcnt(30)
	v_mov_b32_e32 v109, v102
	s_waitcnt vmcnt(28)
	v_mov_b32_e32 v110, v103
	s_waitcnt vmcnt(27)
	v_mov_b32_e32 v111, v104
	s_waitcnt vmcnt(24)
	v_mov_b32_e32 v108, v105
	s_barrier
	s_cbranch_vccz .LBB0_311
	.p2align	6

; __global__ void __launch_bounds__(NWAVES * 64, 2) mk_fwd(Args args) {
;     ...
;             for (int it = F.bid; it < 256; it += F.G) s5_item(F, it);
.LBB0_313:
	s_or_b64 exec, exec, s[4:5]
	s_add_i32 s96, s52, s96
	s_add_i32 s62, s62, s52
	s_cmpk_gt_i32 s96, 0xff
	s_barrier
	s_cbranch_scc1 .LBB0_371
	.p2align	6

; __device__ __forceinline__ unsigned pk2(float lo, float hi) { f32x2_t v = {lo, hi}; bf16x2_t h = __builtin_convertvector(v, bf16x2_t); return __builtin_bit_cast(unsigned, h); }
; __device__ __forceinline__ void hgA_loop(Frame& F, int j0, int j1) {
;     ...
;           v4u w0, w1; w0.x = pk2(acc[0], acc[1]); w0.y = pk2(acc[2], acc[3]); w0.z = pk2(acc[4], acc[5]); w0.w = pk2(acc[6], acc[7]); w1.x = pk2(acc[8], acc[9]); w1.y = pk2(acc[10], acc[11]); w1.z = pk2(acc[12], acc[13]); w1.w = pk2(acc[14], acc[15]);
;           v4u* d = (v4u*)(OI + (size_t)(wave * 64 + lane) * 16); d[0] = w0; d[1] = w1; }
;         __syncthreads();
.LBB0_376:
	s_nop 10
	v_cvt_pk_bf16_f32 v2, v2, v3
	v_cvt_pk_bf16_f32 v3, v4, v5
	v_cvt_pk_bf16_f32 v4, v6, v7
	v_cvt_pk_bf16_f32 v6, v10, v11
	v_lshl_add_u64 v[10:11], s[60:61], 0, v[32:33]
	s_mov_b32 s44, 0x1000000
	v_add_co_u32_e32 v10, vcc, s44, v10
	s_add_i32 s63, s63, s97
	s_add_i32 s10, s10, s11
	s_add_i32 s62, s62, s96
	v_cvt_pk_bf16_f32 v5, v8, v9
	v_cvt_pk_bf16_f32 v8, v14, v15
	v_cvt_pk_bf16_f32 v9, v16, v17
	v_addc_co_u32_e32 v11, vcc, 0, v11, vcc
	s_add_u32 s60, s60, s58
	v_cvt_pk_bf16_f32 v7, v12, v13
	global_store_dwordx4 v[10:11], v[2:5], off
	global_store_dwordx4 v[10:11], v[6:9], off offset:16
	s_addc_u32 s61, s61, s59
	v_lshl_add_u64 v[34:35], v[34:35], 0, s[86:87]
	v_lshl_add_u64 v[36:37], v[36:37], 0, s[4:5]
	s_andn2_b64 vcc, exec, s[54:55]
	s_waitcnt vmcnt(54)
	v_mov_b32_e32 v8, v26
	s_waitcnt vmcnt(52)
	v_mov_b32_e32 v9, v86
	s_waitcnt vmcnt(50)
	v_mov_b32_e32 v10, v88
	s_waitcnt vmcnt(48)
	v_mov_b32_e32 v11, v93
	s_waitcnt vmcnt(46)
	v_mov_b32_e32 v12, v94
	s_waitcnt vmcnt(44)
	v_mov_b32_e32 v13, v95
	s_waitcnt vmcnt(42)
	v_mov_b32_e32 v14, v96
	s_waitcnt vmcnt(40)
	v_mov_b32_e32 v15, v97
	s_waitcnt vmcnt(38)
	v_mov_b32_e32 v16, v98
	s_waitcnt vmcnt(36)
	v_mov_b32_e32 v17, v99
	s_waitcnt vmcnt(34)
	v_mov_b32_e32 v106, v100
	s_waitcnt vmcnt(32)
	v_mov_b32_e32 v107, v101
	s_waitcnt vmcnt(30)
	v_mov_b32_e32 v109, v102
	s_waitcnt vmcnt(28)
	v_mov_b32_e32 v110, v103
	s_waitcnt vmcnt(27)
	v_mov_b32_e32 v111, v104
	s_waitcnt vmcnt(24)
	v_mov_b32_e32 v108, v105
	s_barrier
	s_cbranch_vccz .LBB0_389
	.p2align	6

; __global__ void __launch_bounds__(NWAVES * 64, 2) mk_fwd(Args args) {
;     ...
;             for (int it = F.bid; it < 256; it += F.G) s5_item(F, it);
.LBB0_391:
	s_or_b64 exec, exec, s[4:5]
	s_add_i32 s92, s52, s92
	s_add_i32 s58, s58, s52
	s_cmpk_gt_i32 s92, 0xff
	s_barrier
	s_cbranch_scc1 .LBB0_449
	.p2align	6

; #define LAS __attribute__((address_space(3)))
; __device__ __forceinline__ void hgrn_sample_loop(Frame& F) {
;     ...
;         for (int j = 0; j < 8; ++j) { const int k = 8 * kg + j; const f32x4 sv = s0[j]; const f32x4 qa = *(const LAS f32x4*)(QT + k * 8), qb = *(const LAS f32x4*)(QT + k * 8 + 4), ka = *(const LAS f32x4*)(K3T + k * 8), kb = *(const LAS f32x4*)(K3T + k * 8 + 4);
;             f32x4 sn = sv * DEC[k];
;             o[0] += sv * qa.x; o[1] += sv * qa.y; o[2] += sv * qa.z; o[3] += sv * qa.w; o[4] += sv * qb.x; o[5] += sv * qb.y; o[6] += sv * qb.z; o[7] += sv * qb.w;
;             sn += vr[0] * ka.x; sn += vr[1] * ka.y; sn += vr[2] * ka.z; sn += vr[3] * ka.w; sn += vr[4] * kb.x; sn += vr[5] * kb.y; sn += vr[6] * kb.z; sn += vr[7] * kb.w;
.LBB0_451:
	v_pk_fma_f32 v[176:177], v[30:31], v[70:71], 0 op_sel_hi:[1,0,0]
	v_pk_fma_f32 v[178:179], v[32:33], v[70:71], 0 op_sel_hi:[1,0,0]
	v_pk_fma_f32 v[180:181], v[30:31], v[70:71], 0 op_sel:[0,1,0] op_sel_hi:[1,1,0]
	v_pk_fma_f32 v[70:71], v[32:33], v[70:71], 0 op_sel:[0,1,0] op_sel_hi:[1,1,0]
	v_pk_fma_f32 v[182:183], v[32:33], v[72:73], 0 op_sel_hi:[1,0,0]
	v_pk_fma_f32 v[184:185], v[30:31], v[72:73], 0 op_sel_hi:[1,0,0]
	v_mov_b32_e32 v72, v73
	v_pk_fma_f32 v[194:195], v[32:33], v[68:69], 0 op_sel_hi:[1,0,0]
	v_pk_fma_f32 v[196:197], v[30:31], v[68:69], 0 op_sel_hi:[1,0,0]
	v_mov_b32_e32 v68, v69
	v_pk_fma_f32 v[186:187], v[32:33], v[72:73], 0 op_sel_hi:[1,0,0]
	v_pk_fma_f32 v[72:73], v[30:31], v[72:73], 0 op_sel_hi:[1,0,0]
	v_pk_fma_f32 v[188:189], v[30:31], v[66:67], 0 op_sel_hi:[1,0,0]
	v_pk_fma_f32 v[190:191], v[32:33], v[66:67], 0 op_sel_hi:[1,0,0]
	v_pk_fma_f32 v[192:193], v[30:31], v[66:67], 0 op_sel:[0,1,0] op_sel_hi:[1,1,0]
	v_pk_fma_f32 v[66:67], v[32:33], v[66:67], 0 op_sel:[0,1,0] op_sel_hi:[1,1,0]
	v_pk_fma_f32 v[32:33], v[32:33], v[68:69], 0 op_sel_hi:[1,0,0]
	v_pk_fma_f32 v[30:31], v[30:31], v[68:69], 0 op_sel_hi:[1,0,0]
	v_pk_fma_f32 v[68:69], v[28:29], v[86:87], v[178:179] op_sel_hi:[1,0,1]
	v_pk_fma_f32 v[176:177], v[26:27], v[86:87], v[176:177] op_sel_hi:[1,0,1]
	v_pk_fma_f32 v[70:71], v[28:29], v[86:87], v[70:71] op_sel:[0,1,0]
	v_pk_fma_f32 v[86:87], v[26:27], v[86:87], v[180:181] op_sel:[0,1,0]
	v_pk_fma_f32 v[178:179], v[28:29], v[88:89], v[182:183] op_sel_hi:[1,0,1]
	v_pk_fma_f32 v[180:181], v[26:27], v[88:89], v[184:185] op_sel_hi:[1,0,1]
	v_mov_b32_e32 v88, v89
	v_pk_fma_f32 v[182:183], v[28:29], v[88:89], v[186:187] op_sel_hi:[1,0,1]
	v_pk_fma_f32 v[72:73], v[26:27], v[88:89], v[72:73] op_sel_hi:[1,0,1]
	v_pk_fma_f32 v[88:89], v[28:29], v[74:75], v[190:191] op_sel_hi:[1,0,1]
	v_pk_fma_f32 v[184:185], v[26:27], v[74:75], v[188:189] op_sel_hi:[1,0,1]
	v_pk_fma_f32 v[66:67], v[28:29], v[74:75], v[66:67] op_sel:[0,1,0]
	v_pk_fma_f32 v[74:75], v[26:27], v[74:75], v[192:193] op_sel:[0,1,0]
	v_pk_fma_f32 v[186:187], v[28:29], v[76:77], v[194:195] op_sel_hi:[1,0,1]
	v_pk_fma_f32 v[188:189], v[26:27], v[76:77], v[196:197] op_sel_hi:[1,0,1]
	v_mov_b32_e32 v76, v77
	v_pk_fma_f32 v[28:29], v[28:29], v[76:77], v[32:33] op_sel_hi:[1,0,1]
	v_pk_fma_f32 v[26:27], v[26:27], v[76:77], v[30:31] op_sel_hi:[1,0,1]
	v_pk_fma_f32 v[30:31], v[24:25], v[94:95], v[68:69] op_sel_hi:[1,0,1]
	v_pk_fma_f32 v[32:33], v[22:23], v[94:95], v[176:177] op_sel_hi:[1,0,1]
	v_pk_fma_f32 v[68:69], v[24:25], v[94:95], v[70:71] op_sel:[0,1,0]
	v_pk_fma_f32 v[70:71], v[22:23], v[94:95], v[86:87] op_sel:[0,1,0]
	v_pk_fma_f32 v[76:77], v[22:23], v[96:97], v[180:181] op_sel_hi:[1,0,1]
	v_pk_fma_f32 v[86:87], v[24:25], v[96:97], v[178:179] op_sel_hi:[1,0,1]
	v_mov_b32_e32 v94, v97
	v_pk_fma_f32 v[88:89], v[24:25], v[78:79], v[88:89] op_sel_hi:[1,0,1]
	v_pk_fma_f32 v[96:97], v[22:23], v[78:79], v[184:185] op_sel_hi:[1,0,1]
	v_pk_fma_f32 v[66:67], v[24:25], v[78:79], v[66:67] op_sel:[0,1,0]
	v_pk_fma_f32 v[74:75], v[22:23], v[78:79], v[74:75] op_sel:[0,1,0]
	v_pk_fma_f32 v[78:79], v[22:23], v[80:81], v[188:189] op_sel_hi:[1,0,1]
	v_pk_fma_f32 v[176:177], v[24:25], v[80:81], v[186:187] op_sel_hi:[1,0,1]
	v_mov_b32_e32 v80, v81
	v_pk_fma_f32 v[72:73], v[22:23], v[94:95], v[72:73] op_sel_hi:[1,0,1]
	v_pk_fma_f32 v[94:95], v[24:25], v[94:95], v[182:183] op_sel_hi:[1,0,1]
	v_pk_fma_f32 v[24:25], v[24:25], v[80:81], v[28:29] op_sel_hi:[1,0,1]
	v_pk_fma_f32 v[28:29], v[18:19], v[98:99], v[32:33] op_sel_hi:[1,0,1]
	v_pk_fma_f32 v[32:33], v[18:19], v[98:99], v[70:71] op_sel:[0,1,0]
	v_pk_fma_f32 v[70:71], v[18:19], v[100:101], v[76:77] op_sel_hi:[1,0,1]
	v_mov_b32_e32 v76, v101
	v_pk_fma_f32 v[22:23], v[22:23], v[80:81], v[26:27] op_sel_hi:[1,0,1]
	v_pk_fma_f32 v[26:27], v[20:21], v[98:99], v[30:31] op_sel_hi:[1,0,1]
	v_pk_fma_f32 v[30:31], v[20:21], v[98:99], v[68:69] op_sel:[0,1,0]
	v_pk_fma_f32 v[68:69], v[20:21], v[100:101], v[86:87] op_sel_hi:[1,0,1]
	v_pk_fma_f32 v[80:81], v[20:21], v[76:77], v[94:95] op_sel_hi:[1,0,1]
	v_pk_fma_f32 v[72:73], v[18:19], v[76:77], v[72:73] op_sel_hi:[1,0,1]
	v_pk_fma_f32 v[76:77], v[20:21], v[82:83], v[88:89] op_sel_hi:[1,0,1]
	v_pk_fma_f32 v[86:87], v[18:19], v[82:83], v[96:97] op_sel_hi:[1,0,1]
	v_pk_fma_f32 v[66:67], v[20:21], v[82:83], v[66:67] op_sel:[0,1,0]
	v_pk_fma_f32 v[74:75], v[18:19], v[82:83], v[74:75] op_sel:[0,1,0]
	v_pk_fma_f32 v[82:83], v[20:21], v[84:85], v[176:177] op_sel_hi:[1,0,1]
	v_pk_fma_f32 v[78:79], v[18:19], v[84:85], v[78:79] op_sel_hi:[1,0,1]
	v_mov_b32_e32 v84, v85
	v_pk_fma_f32 v[20:21], v[20:21], v[84:85], v[24:25] op_sel_hi:[1,0,1]
	v_pk_fma_f32 v[24:25], v[14:15], v[102:103], v[28:29] op_sel_hi:[1,0,1]
	v_pk_fma_f32 v[28:29], v[14:15], v[102:103], v[32:33] op_sel:[0,1,0]
	v_pk_fma_f32 v[32:33], v[16:17], v[104:105], v[68:69] op_sel_hi:[1,0,1]
	v_mov_b32_e32 v68, v105
	v_pk_fma_f32 v[18:19], v[18:19], v[84:85], v[22:23] op_sel_hi:[1,0,1]
	v_pk_fma_f32 v[22:23], v[16:17], v[102:103], v[26:27] op_sel_hi:[1,0,1]
	v_pk_fma_f32 v[26:27], v[16:17], v[102:103], v[30:31] op_sel:[0,1,0]
	v_pk_fma_f32 v[30:31], v[14:15], v[104:105], v[70:71] op_sel_hi:[1,0,1]
	v_pk_fma_f32 v[70:71], v[14:15], v[68:69], v[72:73] op_sel_hi:[1,0,1]
	v_pk_fma_f32 v[68:69], v[16:17], v[68:69], v[80:81] op_sel_hi:[1,0,1]
	v_pk_fma_f32 v[80:81], v[16:17], v[92:93], v[82:83] op_sel_hi:[1,0,1]
	v_mov_b32_e32 v82, v93
	v_pk_fma_f32 v[72:73], v[16:17], v[90:91], v[76:77] op_sel_hi:[1,0,1]
	v_pk_fma_f32 v[76:77], v[14:15], v[90:91], v[86:87] op_sel_hi:[1,0,1]
	v_pk_fma_f32 v[66:67], v[16:17], v[90:91], v[66:67] op_sel:[0,1,0]
; #define GAS __attribute__((address_space(1)))
; #define LAS __attribute__((address_space(3)))
; __device__ __forceinline__ void hgrn_sample_loop(Frame& F) {
;     ...
;         for (int j = 0; j < 8; ++j) { const int k = 8 * kg + j; const f32x4 sv = s0[j]; const f32x4 qa = *(const LAS f32x4*)(QT + k * 8), qb = *(const LAS f32x4*)(QT + k * 8 + 4), ka = *(const LAS f32x4*)(K3T + k * 8), kb = *(const LAS f32x4*)(K3T + k * 8 + 4);
;             f32x4 sn = sv * DEC[k];
;             o[0] += sv * qa.x; o[1] += sv * qa.y; o[2] += sv * qa.z; o[3] += sv * qa.w; o[4] += sv * qb.x; o[5] += sv * qb.y; o[6] += sv * qb.z; o[7] += sv * qb.w;
;             sn += vr[0] * ka.x; sn += vr[1] * ka.y; sn += vr[2] * ka.z; sn += vr[3] * ka.w; sn += vr[4] * kb.x; sn += vr[5] * kb.y; sn += vr[6] * kb.z; sn += vr[7] * kb.w;
;             *(GAS f32x4*)(Sout + (size_t)k * HD + v4) = sn; }
;         if (idx + F.G < SB_B * HH) {
; #pragma unroll
;             for (int j = 0; j < 8; ++j) s0[j] = *(const GAS f32x4*)(F.in[4] + (size_t)(idx + F.G) * HD * HD + (size_t)(8 * kg + j) * HD + v4); }
; #pragma unroll
;         for (int t = 0; t < 8; ++t) *(LAS f32x4*)(OP + (kg * 8 + t) * 128 + v4) = o[t];
	v_pk_fma_f32 v[78:79], v[14:15], v[92:93], v[78:79] op_sel_hi:[1,0,1]
	v_pk_fma_f32 v[16:17], v[16:17], v[82:83], v[20:21] op_sel_hi:[1,0,1]
	v_pk_fma_f32 v[20:21], v[10:11], v[110:111], v[24:25] op_sel_hi:[1,0,1]
	v_pk_fma_f32 v[24:25], v[10:11], v[110:111], v[28:29] op_sel:[0,1,0]
	v_pk_fma_f32 v[28:29], v[10:11], v[112:113], v[30:31] op_sel_hi:[1,0,1]
	v_mov_b32_e32 v30, v113
	v_pk_fma_f32 v[74:75], v[14:15], v[90:91], v[74:75] op_sel:[0,1,0]
	v_pk_fma_f32 v[14:15], v[14:15], v[82:83], v[18:19] op_sel_hi:[1,0,1]
	v_pk_fma_f32 v[18:19], v[12:13], v[110:111], v[22:23] op_sel_hi:[1,0,1]
	v_pk_fma_f32 v[22:23], v[12:13], v[110:111], v[26:27] op_sel:[0,1,0]
	v_pk_fma_f32 v[26:27], v[12:13], v[112:113], v[32:33] op_sel_hi:[1,0,1]
	v_pk_fma_f32 v[32:33], v[12:13], v[30:31], v[68:69] op_sel_hi:[1,0,1]
	v_pk_fma_f32 v[30:31], v[10:11], v[30:31], v[70:71] op_sel_hi:[1,0,1]
	v_pk_fma_f32 v[70:71], v[10:11], v[106:107], v[76:77] op_sel_hi:[1,0,1]
	v_pk_fma_f32 v[76:77], v[10:11], v[108:109], v[78:79] op_sel_hi:[1,0,1]
	v_mov_b32_e32 v78, v109
	v_pk_fma_f32 v[68:69], v[12:13], v[106:107], v[72:73] op_sel_hi:[1,0,1]
	v_pk_fma_f32 v[66:67], v[12:13], v[106:107], v[66:67] op_sel:[0,1,0]
	v_pk_fma_f32 v[72:73], v[10:11], v[106:107], v[74:75] op_sel:[0,1,0]
	v_pk_fma_f32 v[74:75], v[12:13], v[108:109], v[80:81] op_sel_hi:[1,0,1]
	v_pk_fma_f32 v[12:13], v[12:13], v[78:79], v[16:17] op_sel_hi:[1,0,1]
	v_pk_fma_f32 v[16:17], v[6:7], v[118:119], v[20:21] op_sel_hi:[1,0,1]
	v_pk_fma_f32 v[20:21], v[6:7], v[118:119], v[24:25] op_sel:[0,1,0]
	v_pk_fma_f32 v[24:25], v[8:9], v[120:121], v[26:27] op_sel_hi:[1,0,1]
	v_mov_b32_e32 v26, v121
	v_pk_fma_f32 v[10:11], v[10:11], v[78:79], v[14:15] op_sel_hi:[1,0,1]
	v_pk_fma_f32 v[14:15], v[8:9], v[118:119], v[18:19] op_sel_hi:[1,0,1]
	v_pk_fma_f32 v[18:19], v[8:9], v[118:119], v[22:23] op_sel:[0,1,0]
	v_pk_fma_f32 v[22:23], v[6:7], v[120:121], v[28:29] op_sel_hi:[1,0,1]
	v_pk_fma_f32 v[28:29], v[6:7], v[26:27], v[30:31] op_sel_hi:[1,0,1]
	v_pk_fma_f32 v[30:31], v[8:9], v[114:115], v[68:69] op_sel_hi:[1,0,1]
	v_pk_fma_f32 v[68:69], v[6:7], v[114:115], v[72:73] op_sel:[0,1,0]
	v_pk_fma_f32 v[72:73], v[8:9], v[116:117], v[74:75] op_sel_hi:[1,0,1]
	v_mov_b32_e32 v74, v117
	v_pk_fma_f32 v[26:27], v[8:9], v[26:27], v[32:33] op_sel_hi:[1,0,1]
	v_pk_fma_f32 v[32:33], v[6:7], v[114:115], v[70:71] op_sel_hi:[1,0,1]
	v_pk_fma_f32 v[66:67], v[8:9], v[114:115], v[66:67] op_sel:[0,1,0]
	v_pk_fma_f32 v[70:71], v[6:7], v[116:117], v[76:77] op_sel_hi:[1,0,1]
	v_pk_fma_f32 v[76:77], v[6:7], v[74:75], v[10:11] op_sel_hi:[1,0,1]
	v_pk_fma_f32 v[74:75], v[8:9], v[74:75], v[12:13] op_sel_hi:[1,0,1]
	v_pk_fma_f32 v[12:13], v[4:5], v[126:127], v[18:19] op_sel:[0,1,0]
	v_mov_b32_e32 v18, v129
	v_pk_fma_f32 v[10:11], v[2:3], v[126:127], v[20:21] op_sel:[0,1,0]
	v_pk_fma_f32 v[20:21], v[4:5], v[18:19], v[26:27] op_sel_hi:[1,0,1]
	v_pk_fma_f32 v[18:19], v[2:3], v[18:19], v[28:29] op_sel_hi:[1,0,1]
	v_pk_fma_f32 v[28:29], v[4:5], v[122:123], v[66:67] op_sel:[0,1,0]
	v_mov_b32_e32 v66, v125
	v_pk_fma_f32 v[8:9], v[4:5], v[126:127], v[14:15] op_sel_hi:[1,0,1]
	v_pk_fma_f32 v[6:7], v[2:3], v[126:127], v[16:17] op_sel_hi:[1,0,1]
	v_pk_fma_f32 v[16:17], v[4:5], v[128:129], v[24:25] op_sel_hi:[1,0,1]
	v_pk_fma_f32 v[14:15], v[2:3], v[128:129], v[22:23] op_sel_hi:[1,0,1]
	v_pk_fma_f32 v[24:25], v[4:5], v[122:123], v[30:31] op_sel_hi:[1,0,1]
	v_pk_fma_f32 v[22:23], v[2:3], v[122:123], v[32:33] op_sel_hi:[1,0,1]
	v_pk_fma_f32 v[26:27], v[2:3], v[122:123], v[68:69] op_sel:[0,1,0]
	v_pk_fma_f32 v[32:33], v[4:5], v[124:125], v[72:73] op_sel_hi:[1,0,1]
	v_pk_fma_f32 v[30:31], v[2:3], v[124:125], v[70:71] op_sel_hi:[1,0,1]
	v_pk_fma_f32 v[4:5], v[4:5], v[66:67], v[74:75] op_sel_hi:[1,0,1]
	v_pk_fma_f32 v[2:3], v[2:3], v[66:67], v[76:77] op_sel_hi:[1,0,1]
	v_add_u32_e32 v66, v144, v130
	ds_write_b128 v66, v[6:9] offset:25344
	ds_write_b128 v66, v[10:13] offset:25856
	ds_write_b128 v66, v[14:17] offset:26368
	ds_write_b128 v66, v[18:21] offset:26880
	ds_write_b128 v66, v[22:25] offset:27392
	ds_write_b128 v66, v[26:29] offset:27904
	ds_write_b128 v66, v[30:33] offset:28416
	ds_write_b128 v66, v[2:5] offset:28928
	s_waitcnt lgkmcnt(0)
	s_barrier
; __device__ __forceinline__ unsigned pk2(float lo, float hi) { f32x2_t v = {lo, hi}; bf16x2_t h = __builtin_convertvector(v, bf16x2_t); return __builtin_bit_cast(unsigned, h); }
; __device__ __forceinline__ float siluf_(float x) { return x * __builtin_amdgcn_rcpf(1.0f + __builtin_amdgcn_exp2f(-1.4426950408889634f * x)); }
; __device__ __forceinline__ void hgrn_sample_loop(Frame& F) {
;     ...
;         __syncthreads();
; #pragma unroll
;         for (int r = 0; r < 2; ++r) { const int e = tid + 512 * r, t = e >> 7, vv = e & 127; float acc = 0.f;
; #pragma unroll
;             for (int g2 = 0; g2 < 16; ++g2) acc += OP[(g2 * 8 + t) * 128 + vv];
; #pragma unroll
;             for (int s = 0; s < 8; ++s) acc += ATT[t * 8 + s] * Vs[s * 128 + vv];
;             OT[t * 128 + vv] = acc; }
;         __syncthreads();
;         { const int t = F.wave, lane = F.lane; const float o0 = OT[t * 128 + 2 * lane], o1 = OT[t * 128 + 2 * lane + 1];
;           const float rstd = __builtin_amdgcn_rsqf(wave_sum(o0 * o0 + o1 * o1) * (1.0f / HD) + EPS);
;           const unsigned gw2 = *(const unsigned*)(PB + (size_t)(tok0 + t) * PBW + 1536 + h * HD + 2 * lane);
;           const float g0 = F.in[17][2 * lane], g1 = F.in[17][2 * lane + 1];
;           *(unsigned*)(MIX + (size_t)(tok0 + t) * DM + 512 + h * HD + 2 * lane) = pk2(o0 * rstd * g0 * siluf_(bflo(gw2)), o1 * rstd * g1 * siluf_(bfhi(gw2))); }
;         __syncthreads();
	ds_read2st64_b32 v[2:3], v166 offset0:99 offset1:115
	ds_read2st64_b32 v[4:5], v166 offset0:131 offset1:147
	ds_read2st64_b32 v[6:7], v166 offset0:163 offset1:179
	s_add_i32 s12, s96, s12
	s_ashr_i32 s13, s12, 31
	s_waitcnt lgkmcnt(2)
	v_add_f32_e32 v2, 0, v2
	v_add_f32_e32 v2, v2, v3
	s_waitcnt lgkmcnt(1)
	v_add_f32_e32 v4, v2, v4
	ds_read2st64_b32 v[2:3], v166 offset0:195 offset1:211
	v_add_f32_e32 v4, v4, v5
	s_waitcnt lgkmcnt(1)
	v_add_f32_e32 v6, v4, v6
	ds_read2st64_b32 v[4:5], v166 offset0:227 offset1:243
	v_add_f32_e32 v6, v6, v7
	s_waitcnt lgkmcnt(1)
	v_add_f32_e32 v2, v6, v2
	ds_read2st64_b32 v[6:7], v167 offset0:160 offset1:176
	v_add_f32_e32 v2, v2, v3
	s_waitcnt lgkmcnt(1)
	v_add_f32_e32 v4, v2, v4
	ds_read2st64_b32 v[2:3], v167 offset0:192 offset1:208
	v_add_f32_e32 v4, v4, v5
	s_waitcnt lgkmcnt(1)
	v_add_f32_e32 v4, v4, v6
	v_add_f32_e32 v4, v4, v7
	ds_read2st64_b32 v[6:7], v167 offset0:224 offset1:240
	s_waitcnt lgkmcnt(1)
	v_add_f32_e32 v2, v4, v2
	v_add_f32_e32 v8, v2, v3
	ds_read_b128 v[2:5], v172 offset:20992
	ds_read2st64_b32 v[10:11], v153 offset0:64 offset1:66
	s_lshl_b64 s[16:17], s[12:13], 12
	s_waitcnt lgkmcnt(2)
	v_add_f32_e32 v6, v8, v6
	v_add_f32_e32 v18, v6, v7
	ds_read2st64_b32 v[12:13], v153 offset0:68 offset1:70
	ds_read_b128 v[6:9], v172 offset:21008
	s_waitcnt lgkmcnt(2)
	v_fmac_f32_e32 v18, v2, v10
	ds_read2st64_b32 v[14:15], v153 offset0:72 offset1:74
	v_fmac_f32_e32 v18, v3, v11
	ds_read2st64_b32 v[2:3], v168 offset0:99 offset1:115
	s_waitcnt lgkmcnt(3)
	v_fmac_f32_e32 v18, v4, v12
	v_fmac_f32_e32 v18, v5, v13
	ds_read2st64_b32 v[4:5], v168 offset0:131 offset1:147
	s_waitcnt lgkmcnt(2)
	v_fmac_f32_e32 v18, v6, v14
	v_fmac_f32_e32 v18, v7, v15
	s_waitcnt lgkmcnt(1)
	v_add_f32_e32 v2, 0, v2
	ds_read2st64_b32 v[6:7], v168 offset0:163 offset1:179
	v_add_f32_e32 v2, v2, v3
	s_waitcnt lgkmcnt(1)
	v_add_f32_e32 v4, v2, v4
	ds_read2st64_b32 v[2:3], v168 offset0:195 offset1:211
	ds_read2st64_b32 v[16:17], v153 offset0:76 offset1:78
	v_add_f32_e32 v4, v4, v5
	s_waitcnt lgkmcnt(2)
	v_add_f32_e32 v6, v4, v6
	ds_read2st64_b32 v[4:5], v168 offset0:227 offset1:243
	v_add_f32_e32 v6, v6, v7
	s_waitcnt lgkmcnt(2)
	v_add_f32_e32 v2, v6, v2
	ds_read2st64_b32 v[6:7], v169 offset0:160 offset1:176
	s_waitcnt lgkmcnt(2)
	v_fmac_f32_e32 v18, v8, v16
	v_fmac_f32_e32 v18, v9, v17
	v_add_f32_e32 v2, v2, v3
	ds_read2st64_b32 v[8:9], v169 offset0:192 offset1:208
	s_waitcnt lgkmcnt(2)
	v_add_f32_e32 v2, v2, v4
	v_add_f32_e32 v2, v2, v5
	ds_write_b32 v145, v18 offset:21248
	s_waitcnt lgkmcnt(2)
	v_add_f32_e32 v2, v2, v6
	ds_read2st64_b32 v[18:19], v169 offset0:224 offset1:240
	v_add_f32_e32 v2, v2, v7
	s_waitcnt lgkmcnt(2)
	v_add_f32_e32 v6, v2, v8
	ds_read_b128 v[2:5], v173 offset:20992
	v_add_f32_e32 v6, v6, v9
	s_waitcnt lgkmcnt(1)
	v_add_f32_e32 v6, v6, v18
	v_add_f32_e32 v18, v6, v19
	ds_read_b128 v[6:9], v173 offset:21008
	s_waitcnt lgkmcnt(1)
	v_fmac_f32_e32 v18, v2, v10
	v_fmac_f32_e32 v18, v3, v11
	v_fmac_f32_e32 v18, v4, v12
	v_fmac_f32_e32 v18, v5, v13
	s_waitcnt lgkmcnt(0)
	v_fmac_f32_e32 v18, v6, v14
	s_add_u32 s16, s56, s16
	v_fmac_f32_e32 v18, v7, v15
	s_addc_u32 s17, s57, s17
	s_lshl_b32 s18, s24, 8
	v_fmac_f32_e32 v18, v8, v16
	s_add_u32 s16, s16, s18
	v_fmac_f32_e32 v18, v9, v17
	s_addc_u32 s17, s17, 0
	ds_write_b32 v145, v18 offset:23296
	s_waitcnt lgkmcnt(0)
	s_barrier
	global_load_dword v8, v132, s[16:17] offset:3072
	global_load_dwordx2 v[2:3], v[134:135], off
	ds_read_b64 v[4:5], v170 offset:21248
	s_lshl_b64 s[12:13], s[12:13], 11
	s_add_u32 s12, s50, s12
	s_addc_u32 s13, s51, s13
	s_add_u32 s12, s12, s18
	s_waitcnt lgkmcnt(0)
	v_pk_mul_f32 v[6:7], v[4:5], v[4:5]
	s_addc_u32 s13, s13, 0
	v_add_f32_e32 v6, v6, v7
	ds_bpermute_b32 v7, v149, v6
	s_waitcnt vmcnt(9)
	v_mov_b64_e32 v[30:31], v[34:35]
	s_waitcnt vmcnt(8)
	v_mov_b64_e32 v[26:27], v[38:39]
	s_waitcnt vmcnt(7)
	v_mov_b64_e32 v[22:23], v[42:43]
	s_waitcnt vmcnt(6)
	v_mov_b64_e32 v[18:19], v[46:47]
	s_waitcnt lgkmcnt(0)
	v_add_f32_e32 v6, v6, v7
	ds_bpermute_b32 v7, v150, v6
	s_waitcnt vmcnt(5)
	v_mov_b64_e32 v[14:15], v[50:51]
	v_lshl_add_u64 v[138:139], v[138:139], 0, s[10:11]
	s_add_i32 s3, s3, s22
	v_lshl_add_u64 v[140:141], v[140:141], 0, s[10:11]
	s_waitcnt lgkmcnt(0)
	v_add_f32_e32 v6, v6, v7
	ds_bpermute_b32 v7, v151, v6
	v_mov_b64_e32 v[32:33], v[36:37]
	v_mov_b64_e32 v[28:29], v[40:41]
	v_mov_b64_e32 v[24:25], v[44:45]
	v_mov_b64_e32 v[20:21], v[48:49]
	s_waitcnt lgkmcnt(0)
	v_add_f32_e32 v6, v6, v7
	ds_bpermute_b32 v7, v155, v6
	v_mov_b64_e32 v[16:17], v[52:53]
	s_waitcnt lgkmcnt(0)
	v_add_f32_e32 v6, v6, v7
	ds_bpermute_b32 v7, v156, v6
	s_waitcnt lgkmcnt(0)
	v_add_f32_e32 v9, v6, v7
	ds_bpermute_b32 v10, v157, v9
	s_waitcnt vmcnt(1)
	v_lshlrev_b32_e32 v6, 16, v8
	v_and_b32_e32 v7, 0xffff0000, v8
	s_waitcnt lgkmcnt(0)
	v_add_f32_e32 v8, v9, v10
	v_mul_f32_e32 v9, 0xbfb8aa3b, v6
	v_exp_f32_e32 v9, v9
	v_mul_f32_e32 v10, 0xbfb8aa3b, v7
	v_exp_f32_e32 v11, v10
	v_fmamk_f32 v8, v8, 0x3c000000, v174
	v_add_f32_e32 v9, 1.0, v9
	v_rsq_f32_e32 v8, v8
	v_rcp_f32_e32 v10, v9
	v_add_f32_e32 v9, 1.0, v11
	v_rcp_f32_e32 v11, v9
	v_pk_mul_f32 v[4:5], v[4:5], v[8:9] op_sel_hi:[1,0]
	s_waitcnt vmcnt(0)
	v_pk_mul_f32 v[2:3], v[2:3], v[4:5]
	v_pk_mul_f32 v[4:5], v[10:11], v[6:7]
	v_mov_b64_e32 v[10:11], v[54:55]
	v_pk_mul_f32 v[2:3], v[2:3], v[4:5]
	v_mov_b64_e32 v[6:7], v[58:59]
	v_cvt_pk_bf16_f32 v4, v2, v3
	v_lshl_add_u64 v[2:3], s[12:13], 0, v[132:133]
	v_add_co_u32_e32 v2, vcc, 0xc500000, v2
	v_mov_b64_e32 v[12:13], v[56:57]
	s_nop 0
	v_addc_co_u32_e32 v3, vcc, 0, v3, vcc
	global_store_dword v[2:3], v4, off offset:1024
	v_mov_b64_e32 v[2:3], v[62:63]
	s_and_b64 vcc, exec, s[14:15]
	v_mov_b64_e32 v[8:9], v[60:61]
	v_mov_b64_e32 v[4:5], v[64:65]
	s_barrier
	s_cbranch_vccnz .LBB0_462
	.p2align	6

; __device__ __forceinline__ unsigned pk2(float lo, float hi) { f32x2_t v = {lo, hi}; bf16x2_t h = __builtin_convertvector(v, bf16x2_t); return __builtin_bit_cast(unsigned, h); }
; __device__ __forceinline__ void hgA_loop(Frame& F, int j0, int j1) {
;     ...
;           v4u w0, w1; w0.x = pk2(acc[0], acc[1]); w0.y = pk2(acc[2], acc[3]); w0.z = pk2(acc[4], acc[5]); w0.w = pk2(acc[6], acc[7]); w1.x = pk2(acc[8], acc[9]); w1.y = pk2(acc[10], acc[11]); w1.z = pk2(acc[12], acc[13]); w1.w = pk2(acc[14], acc[15]);
;           v4u* d = (v4u*)(OI + (size_t)(wave * 64 + lane) * 16); d[0] = w0; d[1] = w1; }
;         __syncthreads();
;     }
.LBB0_525:
	s_nop 10
	v_cvt_pk_bf16_f32 v2, v2, v3
	v_cvt_pk_bf16_f32 v3, v4, v5
	v_cvt_pk_bf16_f32 v4, v6, v7
	v_cvt_pk_bf16_f32 v6, v10, v11
	v_lshl_add_u64 v[10:11], s[60:61], 0, v[32:33]
	s_mov_b32 s44, 0x1000000
	v_add_co_u32_e32 v10, vcc, s44, v10
	s_add_i32 s55, s55, s62
	s_add_i32 s63, s63, s89
	s_add_i32 s54, s54, s88
	v_cvt_pk_bf16_f32 v5, v8, v9
	v_cvt_pk_bf16_f32 v8, v14, v15
	v_cvt_pk_bf16_f32 v9, v16, v17
	v_addc_co_u32_e32 v11, vcc, 0, v11, vcc
	s_add_u32 s60, s60, s58
	v_cvt_pk_bf16_f32 v7, v12, v13
	global_store_dwordx4 v[10:11], v[2:5], off
	global_store_dwordx4 v[10:11], v[6:9], off offset:16
	s_addc_u32 s61, s61, s59
	v_lshl_add_u64 v[34:35], v[34:35], 0, s[84:85]
	v_lshl_add_u64 v[36:37], v[36:37], 0, s[86:87]
	s_andn2_b64 vcc, exec, s[4:5]
	s_waitcnt vmcnt(54)
	v_mov_b32_e32 v8, v26
	s_waitcnt vmcnt(52)
	v_mov_b32_e32 v9, v88
	s_waitcnt vmcnt(50)
	v_mov_b32_e32 v10, v90
	s_waitcnt vmcnt(48)
	v_mov_b32_e32 v11, v93
	s_waitcnt vmcnt(46)
	v_mov_b32_e32 v12, v95
	s_waitcnt vmcnt(44)
	v_mov_b32_e32 v13, v96
	s_waitcnt vmcnt(42)
	v_mov_b32_e32 v14, v97
	s_waitcnt vmcnt(40)
	v_mov_b32_e32 v15, v98
	s_waitcnt vmcnt(38)
	v_mov_b32_e32 v16, v99
	s_waitcnt vmcnt(36)
	v_mov_b32_e32 v17, v100
	s_waitcnt vmcnt(34)
	v_mov_b32_e32 v107, v101
	s_waitcnt vmcnt(32)
	v_mov_b32_e32 v108, v102
	s_waitcnt vmcnt(30)
	v_mov_b32_e32 v110, v103
	s_waitcnt vmcnt(28)
	v_mov_b32_e32 v111, v104
	s_waitcnt vmcnt(27)
	v_mov_b32_e32 v112, v105
	s_waitcnt vmcnt(24)
	v_mov_b32_e32 v109, v106
	s_barrier
	s_cbranch_vccz .LBB0_538
	.p2align	6

; #define LAS __attribute__((address_space(3)))
; __device__ __forceinline__ void hg_scan(Frame& F, bf16* DSO, int sb, int nsb) {
;     ...
;     for (int T0 = sb * 512; T0 < 32 * 4096; T0 += nsb * 512) {
;         const int T = T0 + F.tid, bh = T0 >> 12, e = T & 4095, v = e >> 5, k4 = (e & 31) * 4;
;         v2u x[32];
; #pragma unroll
;         for (int c = 0; c < 32; ++c) x[c] = *(const v2u*)(DSC + ((size_t)(bh * 32 + c) * HD + v) * HD + k4);
; #pragma unroll
;         for (int i = 0; i < 2; ++i) { const int p = F.tid + 512 * i; *(LAS f32x4*)(DL + p * 4) = *(const f32x4*)(DEC + (size_t)bh * 32 * HD + p * 4); }
.LBB0_607:
	v_readlane_b32 s0, v238, 0
	v_readlane_b32 s1, v238, 1
	s_cmp_lt_i32 s0, 4
	s_cselect_b64 s[0:1], -1, 0
	s_and_b64 s[0:1], s[0:1], s[4:5]
	s_andn2_b64 vcc, exec, s[0:1]
	s_cbranch_vccnz .LBB0_611
	s_cmpk_gt_i32 s2, 0xff
	s_cbranch_scc1 .LBB0_611
	v_lshlrev_b32_e32 v2, 2, v0
	v_and_b32_e32 v6, 0x7c, v2
	v_lshlrev_b32_e32 v2, 1, v6
	v_mov_b32_e32 v3, 0
	v_lshl_add_u64 v[4:5], s[46:47], 0, v[2:3]
	v_lshlrev_b32_e32 v2, 9, v6
	v_lshlrev_b32_e32 v8, 4, v0
	v_lshl_add_u32 v71, v6, 2, 0
	v_lshl_add_u64 v[6:7], s[48:49], 0, v[2:3]
	s_mov_b64 s[4:5], 0x4420000
	v_mov_b32_e32 v9, v3
	v_add_u32_e32 v70, 0, v8
	v_lshl_add_u64 v[6:7], v[6:7], 0, s[4:5]
	v_lshl_add_u64 v[8:9], s[50:51], 0, v[8:9]
	s_mov_b64 s[4:5], 0x100000
	s_lshl_b32 s3, s2, 9
	s_lshl_b32 s8, s52, 9
	v_lshl_add_u64 v[8:9], v[8:9], 0, s[4:5]
	s_movk_i32 s9, 0x2000
	v_mov_b32_e32 v72, v3
	v_mov_b32_e32 v73, v3
	.p2align	6

; #define PG8_BAR __builtin_amdgcn_s_barrier()
; template <class Epi, class Sched, bool ALIGN_EPI = false, bool SP2 = false, bool AGM = false  >
; __device__ __forceinline__ void gemm_phase(PG8_LAS unsigned char* lds, const Gemm g, const Sched& S, const Epi& E) {
;     ...
;         if (!has_next) break;
; #pragma unroll
;         for (int a = 0; a < 2; ++a)
; #pragma unroll
;             for (int b = 0; b < 2; ++b)
; #pragma unroll
;                 for (int m = 0; m < 4; ++m)
; #pragma unroll
;                     for (int n = 0; n < 2; ++n) acc[a][b][m][n] = (f32x4){0.f, 0.f, 0.f, 0.f};
;         cur = nxt; cA = nA; cB = nB; ++ui;
;         if constexpr (ALIGN_EPI) { if (wr == 1) PG8_BAR; }
;     }
.LBB0_673:
	s_andn2_b64 vcc, exec, s[0:1]
	s_mov_b32 s33, s16
	s_mov_b32 s4, s18
	s_mov_b64 s[26:27], s[22:23]
	s_mov_b64 s[24:25], s[20:21]
	s_cbranch_vccz .LBB0_683
	.p2align	6

; __device__ __forceinline__ void hgC_loop(Frame& F, unsigned* ctr) {
;     ...
;     if (tid == 0) { slot[0] = (int)__hip_atomic_fetch_add(ctr, 1u, __ATOMIC_RELAXED, __HIP_MEMORY_SCOPE_AGENT); slot[1] = (int)__hip_atomic_fetch_add(ctr, 1u, __ATOMIC_RELAXED, __HIP_MEMORY_SCOPE_AGENT); }
;     __syncthreads();
;     int item = slot[0], nxt = slot[1], par = 0;
;     if (item >= 1024) return;
;     v4u sc[4], qh[2], oi[2]; v2u og[4];
;     ...
;     HGC_FETCH(item);
.LBB0_690:
	s_or_b64 exec, exec, s[0:1]
	v_mov_b32_e32 v55, 0
	s_waitcnt lgkmcnt(0)
	s_barrier
	ds_read_b32 v2, v55 offset:53248
	ds_read_b32 v3, v55 offset:53252
	s_movk_i32 s0, 0x3ff
	s_mov_b32 s11, 0
	s_waitcnt lgkmcnt(1)
	v_cmp_lt_i32_e32 vcc, s0, v2
	v_readfirstlane_b32 s18, v2
	s_waitcnt lgkmcnt(0)
	v_readfirstlane_b32 s17, v3
	s_cbranch_vccnz .LBB0_701
	s_lshl_b32 s0, s96, 3
	v_and_b32_e32 v12, 31, v0
	v_readlane_b32 s20, v238, 25
	s_and_b32 s0, s0, 0x1fffffe0
	s_ashr_i32 s19, s18, 31
	s_bfe_u32 s3, s20, 0x20006
	v_or_b32_e32 v90, s0, v12
	s_lshl_b64 s[0:1], s[18:19], 15
	s_add_u32 s0, s46, s0
	v_lshlrev_b32_e32 v2, 4, v0
	v_or_b32_e32 v6, 0x200, v0
	s_addc_u32 s1, s47, s1
	v_and_b32_e32 v54, 0xf0, v2
	v_lshrrev_b32_e32 v14, 4, v6
	v_lshl_add_u64 v[2:3], s[0:1], 0, v[54:55]
	v_lshlrev_b32_e32 v56, 8, v139
	v_mov_b32_e32 v57, v55
	v_lshlrev_b32_e32 v58, 8, v14
	v_mov_b32_e32 v59, v55
	s_lshl_b64 s[14:15], s[18:19], 14
	v_lshl_add_u64 v[4:5], v[2:3], 0, v[56:57]
	v_lshl_add_u64 v[6:7], v[2:3], 0, v[58:59]
	s_add_u32 s12, s48, 0x1000000
	global_load_dwordx4 v[18:21], v[4:5], off
	global_load_dwordx4 v[22:25], v[6:7], off
	v_or_b32_e32 v6, 0x600, v0
	s_addc_u32 s13, s49, 0
	s_lshl_b32 s10, s18, 4
	s_lshl_b32 s16, s18, 6
	v_lshrrev_b32_e32 v15, 4, v6
	v_or_b32_e32 v60, 0x4000, v56
	v_mov_b32_e32 v61, v55
	v_lshlrev_b32_e32 v62, 8, v15
	v_mov_b32_e32 v63, v55
	s_add_u32 s0, s48, s14
	v_lshl_add_u64 v[4:5], v[2:3], 0, v[60:61]
	v_lshl_add_u64 v[2:3], v[2:3], 0, v[62:63]
	s_addc_u32 s1, s49, s15
	s_and_b32 s10, s10, 0xfffff800
	global_load_dwordx4 v[26:29], v[4:5], off
	global_load_dwordx4 v[30:33], v[2:3], off
	v_lshl_add_u64 v[2:3], s[0:1], 0, v[54:55]
	s_add_u32 s0, s12, s14
	v_lshl_add_u64 v[4:5], v[2:3], 0, v[56:57]
	v_lshl_add_u64 v[2:3], v[2:3], 0, v[58:59]
	s_addc_u32 s1, s13, s15
	s_and_b32 s15, s20, 0xffffffc0
	global_load_dwordx4 v[34:37], v[4:5], off
	global_load_dwordx4 v[38:41], v[2:3], off
	v_or_b32_e32 v2, s15, v154
	v_mov_b32_e32 v3, v55
	s_and_b32 s14, s16, 0x7c0
	v_lshlrev_b64 v[2:3], 5, v[2:3]
	v_lshl_add_u64 v[4:5], s[0:1], 0, v[2:3]
	s_or_b32 s0, s10, s14
	global_load_dwordx4 v[50:53], v[4:5], off offset:16
	global_load_dwordx4 v[6:9], v[4:5], off
	v_add_u32_e32 v4, s0, v90
	v_ashrrev_i32_e32 v5, 31, v4
	v_lshlrev_b64 v[4:5], 12, v[4:5]
	s_lshl_b32 s0, s18, 3
	v_lshl_add_u64 v[4:5], s[56:57], 0, v[4:5]
	s_and_b32 s10, s0, 0x300
	v_lshrrev_b32_e32 v13, 5, v154
	v_lshl_add_u64 v[4:5], v[4:5], 0, s[10:11]
	s_lshl_b32 s10, s3, 6
	v_lshl_add_u64 v[4:5], v[4:5], 0, s[10:11]
	v_lshlrev_b32_e32 v10, 3, v13
	v_mov_b32_e32 v11, v55
	v_lshl_add_u64 v[4:5], v[4:5], 0, v[10:11]
	global_load_dwordx2 v[80:81], v[4:5], off offset:3072
	global_load_dwordx2 v[78:79], v[4:5], off offset:3088
	global_load_dwordx2 v[76:77], v[4:5], off offset:3104
	global_load_dwordx2 v[70:71], v[4:5], off offset:3120
	s_lshl_b32 s10, s3, 5
	s_lshl_b32 s0, s3, 2
	v_or_b32_e32 v10, s10, v12
	s_add_i32 s3, s0, 0
	s_movk_i32 s0, 0x110
	v_mul_u32_u24_e32 v10, 0x110, v10
	v_lshlrev_b32_e32 v11, 4, v13
	v_lshlrev_b32_e32 v4, 2, v13
	v_add3_u32 v91, 0, v10, v11
	v_mul_lo_u32 v10, v90, s0
	v_add3_u32 v92, 0, v10, v11
	v_or_b32_e32 v10, s10, v4
	v_readlane_b32 s68, v238, 29
	v_add_u32_e32 v5, 0, v54
	v_mul_u32_u24_e32 v11, 0x110, v139
	v_mul_u32_u24_e32 v12, 0x110, v14
	v_mul_u32_u24_e32 v13, 0x110, v15
	v_lshl_add_u64 v[64:65], s[46:47], 0, v[54:55]
	v_lshl_add_u64 v[66:67], s[48:49], 0, v[54:55]
	v_lshl_add_u64 v[68:69], s[12:13], 0, v[2:3]
	v_lshlrev_b32_e32 v54, 2, v10
	v_readlane_b32 s70, v238, 31
	v_readlane_b32 s71, v238, 32
	v_mbcnt_lo_u32_b32 v2, -1, 0
	v_cmp_gt_u32_e64 s[0:1], 32, v154
	v_lshlrev_b32_e32 v93, 4, v90
	v_lshl_add_u64 v[72:73], s[70:71], 0, v[54:55]
	global_load_dwordx4 v[198:201], v[72:73], off
	global_load_dwordx4 v[202:205], v[72:73], off offset:32
	global_load_dwordx4 v[206:209], v[72:73], off offset:64
	global_load_dwordx4 v[210:213], v[72:73], off offset:96
	v_add_u32_e32 v94, v5, v11
	v_add_u32_e32 v95, v5, v12
	v_add_u32_e32 v96, v5, v13
	s_lshl_b32 s12, s10, 1
	v_lshlrev_b32_e32 v74, 1, v4
	v_mbcnt_hi_u32_b32 v97, -1, v2
	v_mov_b32_e32 v98, 0x358637bd
	v_lshlrev_b32_e32 v54, 1, v10
	s_mov_b64 s[14:15], 0xc500400
	s_mov_b32 s19, 0xc500000
	v_mov_b32_e32 v99, v55
	v_readlane_b32 s69, v238, 30
	v_readlane_b32 s72, v238, 33
	v_readlane_b32 s73, v238, 34
	v_readlane_b32 s74, v238, 35
	v_readlane_b32 s75, v238, 36
	v_readlane_b32 s76, v238, 37
	v_readlane_b32 s77, v238, 38
	v_readlane_b32 s78, v238, 39
	v_readlane_b32 s79, v238, 40
	v_readlane_b32 s80, v238, 41
	v_readlane_b32 s81, v238, 42
	v_readlane_b32 s82, v238, 43
	v_readlane_b32 s83, v238, 44
	s_branch .LBB0_693
	.p2align	6
